# differential attention QK: K-fragment LDS reads for 3 of the 4 k-steps issued up front (third fragment buffer), on top of the dilated-loop version
# speedup vs baseline: 1.0064x; 1.0064x over previous
; #define LAS __attribute__((address_space(3)))
; #define MFMA32(a, b, c) __builtin_amdgcn_mfma_f32_32x32x16_bf16((a), (b), (c), 0, 0, 0)
; template <int KSTEPS, class Pol>
; __device__ __forceinline__ void attn_pass(LAS unsigned char* lds, const Pol& P, const bf16_t* qb, int ldq, const bf16_t* kb, int ldk, const bf16_t* vb, int ldv,
;                                           float qs, f32x16 (&O)[4], float& m, float& l) {
;     ...
;         LAS unsigned char* Kb = lds + st * A_STAGE + krow;
;         f32x16 S0, S1;
;         P.fill(S0, S1, qi, half, t, wave);
; #pragma unroll
;         for (int ks = 0; ks < KSTEPS; ++ks) {
;             const int so = ((2 * ks) ^ kx) << 4;
;             const bf16x8 a0 = *(const LAS bf16x8*)(Kb + so);
;             const bf16x8 a1 = *(const LAS bf16x8*)(Kb + 32 * KROWB + so);
;             S0 = MFMA32(a0, qf[ks], S0);
;             S1 = MFMA32(a1, qf[ks], S1);
;         }
;         S0 = S0 * qs; S1 = S1 * qs;
;         float mx = fmaxf(S0[0], S1[0]);
; #pragma unroll
;         for (int i = 1; i < 16; ++i) mx = fmaxf(fmaxf(mx, S0[i]), S1[i]);
;         mx = fmaxf(mx, __shfl_xor(mx, 32));
;         const float mnew = fmaxf(m, mx);
;         const float alpha = __builtin_amdgcn_exp2f(m - mnew);
;         m = mnew;
.LBB0_505:
	s_add_i32 s36, s51, 0
	v_add_u32_e32 v0, s36, v151
	v_add_u32_e32 v200, v0, v152
	ds_read_b128 v[192:195], v200
	ds_read_b128 v[196:199], v200 offset:4096
	v_add_u32_e32 v6, v0, v153
	ds_read_b128 v[2:5], v6
	ds_read_b128 v[6:9], v6 offset:4096
	v_add_u32_e32 v205, v0, v155
	ds_read_b128 v[208:211], v205
	ds_read_b128 v[212:215], v205 offset:4096
	s_mov_b32 s40, 0x3e38aa3b
	s_waitcnt lgkmcnt(5)
	v_mfma_f32_32x32x16_bf16 v[80:95], v[192:195], v[112:115], v[80:95]
	s_waitcnt lgkmcnt(4)
	v_mfma_f32_32x32x16_bf16 v[96:111], v[196:199], v[112:115], v[96:111]
	v_add_u32_e32 v200, v0, v156
	ds_read_b128 v[192:195], v200
	ds_read_b128 v[196:199], v200 offset:4096
	s_waitcnt lgkmcnt(5)
	v_mfma_f32_32x32x16_bf16 v[80:95], v[2:5], v[116:119], v[80:95]
	s_waitcnt lgkmcnt(4)
	v_mfma_f32_32x32x16_bf16 v[96:111], v[6:9], v[116:119], v[96:111]
	s_waitcnt lgkmcnt(3)
	v_mfma_f32_32x32x16_bf16 v[80:95], v[208:211], v[120:123], v[80:95]
	s_waitcnt lgkmcnt(2)
	v_mfma_f32_32x32x16_bf16 v[96:111], v[212:215], v[120:123], v[96:111]
	s_waitcnt lgkmcnt(1)
	v_mfma_f32_32x32x16_bf16 v[80:95], v[192:195], v[124:127], v[80:95]
	s_waitcnt lgkmcnt(0)
	v_mfma_f32_32x32x16_bf16 v[96:111], v[196:199], v[124:127], v[96:111]
	v_add_u32_e32 v7, s36, v158
	v_add_u32_e32 v139, s36, v159
	v_add_u32_e32 v142, s36, v160
	v_add_u32_e32 v143, s36, v161
	v_add_u32_e32 v146, s36, v162
	v_add_u32_e32 v147, s36, v163
	v_add_u32_e32 v169, s36, v164
	v_add_u32_e32 v170, s36, v165
	ds_read_b64_tr_b16 v[176:177], v7 offset:16384
	ds_read_b64_tr_b16 v[178:179], v139 offset:2048
	ds_read_b64_tr_b16 v[180:181], v142 offset:16384
	ds_read_b64_tr_b16 v[182:183], v143 offset:2048
	ds_read_b64_tr_b16 v[192:193], v146 offset:16384
	ds_read_b64_tr_b16 v[194:195], v147 offset:2048
	ds_read_b64_tr_b16 v[196:197], v169 offset:16384
	ds_read_b64_tr_b16 v[198:199], v170 offset:2048
	v_max_f32_e32 v0, v80, v96
	v_max3_f32 v0, v0, v81, v97
	v_max3_f32 v0, v0, v82, v98
	v_max3_f32 v0, v0, v83, v99
	v_max3_f32 v0, v0, v84, v100
	v_max3_f32 v0, v0, v85, v101
	v_max3_f32 v0, v0, v86, v102
	v_max3_f32 v0, v0, v87, v103
	v_max3_f32 v0, v0, v88, v104
	v_max3_f32 v0, v0, v89, v105
	v_max3_f32 v0, v0, v90, v106
	v_max3_f32 v0, v0, v91, v107
	v_max3_f32 v0, v0, v92, v108
	v_max3_f32 v0, v0, v93, v109
	v_max3_f32 v0, v0, v94, v110
	v_max3_f32 v0, v0, v95, v111
	v_mul_f32_e64 v0, v0, s40
	ds_bpermute_b32 v6, v148, v0
	s_waitcnt lgkmcnt(0)
	v_max3_f32 v0, v167, v0, v6
	v_sub_f32_e32 v6, v167, v0
	v_exp_f32_e32 v6, v6
	s_nop 0
	v_cmp_neq_f32_e32 vcc, 1.0, v6
	s_cbranch_vccz .LBB0_507
	v_pk_mul_f32 v[78:79], v[78:79], v[6:7] op_sel_hi:[1,0]
	v_pk_mul_f32 v[76:77], v[76:77], v[6:7] op_sel_hi:[1,0]
	v_pk_mul_f32 v[74:75], v[74:75], v[6:7] op_sel_hi:[1,0]
	v_pk_mul_f32 v[72:73], v[72:73], v[6:7] op_sel_hi:[1,0]
	v_pk_mul_f32 v[70:71], v[70:71], v[6:7] op_sel_hi:[1,0]
	v_pk_mul_f32 v[68:69], v[68:69], v[6:7] op_sel_hi:[1,0]
	v_pk_mul_f32 v[66:67], v[66:67], v[6:7] op_sel_hi:[1,0]
	v_pk_mul_f32 v[64:65], v[64:65], v[6:7] op_sel_hi:[1,0]
	v_pk_mul_f32 v[62:63], v[62:63], v[6:7] op_sel_hi:[1,0]
	v_pk_mul_f32 v[60:61], v[60:61], v[6:7] op_sel_hi:[1,0]
	v_pk_mul_f32 v[58:59], v[58:59], v[6:7] op_sel_hi:[1,0]
	v_pk_mul_f32 v[56:57], v[56:57], v[6:7] op_sel_hi:[1,0]
	v_pk_mul_f32 v[54:55], v[54:55], v[6:7] op_sel_hi:[1,0]
	v_pk_mul_f32 v[52:53], v[52:53], v[6:7] op_sel_hi:[1,0]
	v_pk_mul_f32 v[50:51], v[50:51], v[6:7] op_sel_hi:[1,0]
	v_pk_mul_f32 v[48:49], v[48:49], v[6:7] op_sel_hi:[1,0]
	v_pk_mul_f32 v[46:47], v[46:47], v[6:7] op_sel_hi:[1,0]
	v_pk_mul_f32 v[44:45], v[44:45], v[6:7] op_sel_hi:[1,0]
	v_pk_mul_f32 v[42:43], v[42:43], v[6:7] op_sel_hi:[1,0]
	v_pk_mul_f32 v[40:41], v[40:41], v[6:7] op_sel_hi:[1,0]
	v_pk_mul_f32 v[38:39], v[38:39], v[6:7] op_sel_hi:[1,0]
	v_pk_mul_f32 v[36:37], v[36:37], v[6:7] op_sel_hi:[1,0]
	v_pk_mul_f32 v[34:35], v[34:35], v[6:7] op_sel_hi:[1,0]
	v_pk_mul_f32 v[32:33], v[32:33], v[6:7] op_sel_hi:[1,0]
	v_pk_mul_f32 v[30:31], v[30:31], v[6:7] op_sel_hi:[1,0]
	v_pk_mul_f32 v[28:29], v[28:29], v[6:7] op_sel_hi:[1,0]
	v_pk_mul_f32 v[26:27], v[26:27], v[6:7] op_sel_hi:[1,0]
	v_pk_mul_f32 v[24:25], v[24:25], v[6:7] op_sel_hi:[1,0]
	v_pk_mul_f32 v[22:23], v[22:23], v[6:7] op_sel_hi:[1,0]
	v_pk_mul_f32 v[20:21], v[20:21], v[6:7] op_sel_hi:[1,0]
	v_pk_mul_f32 v[18:19], v[18:19], v[6:7] op_sel_hi:[1,0]
	v_pk_mul_f32 v[16:17], v[16:17], v[6:7] op_sel_hi:[1,0]
